# stack8: stack6 + P5 sample-path group barrier: early invalidate behind the arrival atomic, duplicate barrier dropped (stores and wbl2 unchanged)
# baseline (speedup 1.0000x reference)
.LBB0_723:
	s_add_u32 s2, s66, 0x11000000
	s_addc_u32 s3, s67, 0
	s_lshl_b32 s0, s15, 22
	s_add_u32 s6, s2, s0
	s_addc_u32 s7, s3, 0
	s_lshl_b32 s0, s4, 8
	s_addk_i32 s0, 0xc000
	v_or_b32_e32 v128, s0, v128
	v_add_u32_e32 v130, s5, v128
	v_lshl_or_b32 v128, s1, 8, v129
	v_ashrrev_i32_e32 v131, 31, v130
	v_or_b32_e32 v134, s16, v128
	v_lshlrev_b64 v[128:129], 12, v[130:131]
	v_lshl_add_u64 v[132:133], s[6:7], 0, v[128:129]
	v_lshlrev_b32_e32 v128, 2, v134
	v_mov_b32_e32 v129, 0
	v_lshl_add_u64 v[132:133], v[132:133], 0, v[128:129]
	global_store_dwordx4 v[132:133], v[40:43], off
	global_store_dwordx4 v[132:133], v[44:47], off offset:16
	global_store_dwordx4 v[132:133], v[88:91], off offset:512
	global_store_dwordx4 v[132:133], v[92:95], off offset:528
	v_or_b32_e32 v40, 16, v130
	v_ashrrev_i32_e32 v41, 31, v40
	v_lshlrev_b64 v[40:41], 12, v[40:41]
	v_lshl_add_u64 v[40:41], s[6:7], 0, v[40:41]
	v_lshl_add_u64 v[40:41], v[40:41], 0, v[128:129]
	global_store_dwordx4 v[40:41], v[16:19], off
	global_store_dwordx4 v[40:41], v[20:23], off offset:16
	global_store_dwordx4 v[40:41], v[64:67], off offset:512
	global_store_dwordx4 v[40:41], v[68:71], off offset:528
	v_or_b32_e32 v16, 32, v130
	v_ashrrev_i32_e32 v17, 31, v16
	v_lshlrev_b64 v[16:17], 12, v[16:17]
	v_lshl_add_u64 v[16:17], s[6:7], 0, v[16:17]
	v_lshl_add_u64 v[16:17], v[16:17], 0, v[128:129]
	global_store_dwordx4 v[16:17], v[8:11], off
	global_store_dwordx4 v[16:17], v[12:15], off offset:16
	global_store_dwordx4 v[16:17], v[48:51], off offset:512
	global_store_dwordx4 v[16:17], v[56:59], off offset:528
	v_or_b32_e32 v8, 48, v130
	v_ashrrev_i32_e32 v9, 31, v8
	v_lshlrev_b64 v[8:9], 12, v[8:9]
	v_lshl_add_u64 v[8:9], s[6:7], 0, v[8:9]
	v_lshl_add_u64 v[8:9], v[8:9], 0, v[128:129]
	s_mov_b64 s[0:1], 0x80000
	global_store_dwordx4 v[8:9], v[0:3], off
	global_store_dwordx4 v[8:9], v[4:7], off offset:16
	global_store_dwordx4 v[8:9], v[24:27], off offset:512
	global_store_dwordx4 v[8:9], v[32:35], off offset:528
	v_lshl_add_u64 v[0:1], v[132:133], 0, s[0:1]
	s_mov_b32 s0, 0x80000
	v_add_co_u32_e32 v2, vcc, s0, v132
	s_mov_b64 s[0:1], 0x90000
	s_nop 0
	v_addc_co_u32_e32 v3, vcc, 0, v133, vcc
	global_store_dwordx4 v[2:3], v[96:99], off
	global_store_dwordx4 v[0:1], v[100:103], off offset:16
	global_store_dwordx4 v[0:1], v[120:123], off offset:512
	global_store_dwordx4 v[0:1], v[124:127], off offset:528
	v_lshl_add_u64 v[0:1], v[132:133], 0, s[0:1]
	s_mov_b32 s0, 0x90000
	v_add_co_u32_e32 v2, vcc, s0, v132
	s_mov_b64 s[0:1], 0xa0000
	s_nop 0
	v_addc_co_u32_e32 v3, vcc, 0, v133, vcc
	global_store_dwordx4 v[2:3], v[72:75], off
	global_store_dwordx4 v[0:1], v[76:79], off offset:16
	global_store_dwordx4 v[0:1], v[112:115], off offset:512
	global_store_dwordx4 v[0:1], v[116:119], off offset:528
	v_lshl_add_u64 v[0:1], v[132:133], 0, s[0:1]
	s_mov_b32 s0, 0xa0000
	v_add_co_u32_e32 v2, vcc, s0, v132
	s_mov_b64 s[0:1], 0xb0000
	s_nop 0
	v_addc_co_u32_e32 v3, vcc, 0, v133, vcc
	global_store_dwordx4 v[2:3], v[52:55], off
	global_store_dwordx4 v[0:1], v[60:63], off offset:16
	global_store_dwordx4 v[0:1], v[104:107], off offset:512
	global_store_dwordx4 v[0:1], v[108:111], off offset:528
	v_add_co_u32_e32 v2, vcc, 0xb0000, v132
	v_lshl_add_u64 v[0:1], v[132:133], 0, s[0:1]
	s_nop 0
	v_addc_co_u32_e32 v3, vcc, 0, v133, vcc
	global_store_dwordx4 v[2:3], v[28:31], off
	global_store_dwordx4 v[0:1], v[36:39], off offset:16
	global_store_dwordx4 v[0:1], v[80:83], off offset:512
	global_store_dwordx4 v[0:1], v[84:87], off offset:528
	s_and_b64 vcc, exec, s[72:73]
	s_waitcnt vmcnt(0)
	s_barrier
	s_cbranch_vccnz .LBB0_742
	v_mbcnt_lo_u32_b32 v0, -1, 0
	v_mbcnt_hi_u32_b32 v0, -1, v0
	s_nop 0
	v_cmp_eq_u32_e32 vcc, 0, v0
	s_and_saveexec_b64 s[0:1], vcc
	s_cbranch_execz .LBB0_741
	s_lshl_b32 s4, s14, 6
	s_ashr_i32 s5, s4, 31
	s_lshl_b64 s[4:5], s[4:5], 2
	s_mov_b64 s[6:7], exec
	s_add_u32 s4, s66, s4
	s_addc_u32 s5, s67, s5
	buffer_wbl2 sc1
	s_waitcnt vmcnt(0)
	v_mbcnt_lo_u32_b32 v0, s6, 0
	s_add_u32 s4, s4, 0x8000
	v_mbcnt_hi_u32_b32 v0, s7, v0
	s_addc_u32 s5, s5, 0
	v_cmp_eq_u32_e32 vcc, 0, v0
	s_and_saveexec_b64 s[8:9], vcc
	s_cbranch_execz .LBB0_727
	s_bcnt1_i32_b64 s6, s[6:7]
	v_mov_b32_e32 v0, 0
	v_mov_b32_e32 v1, s6
	global_atomic_add v0, v1, s[4:5]
